# attention: staging global loads issued inside the next QK segment; K-publishing barrier no longer waits for the V LDS writes
# baseline (speedup 1.0000x reference)
; #define KFRAG(d0, which) (*reinterpret_cast<const bf16x8*>(Ks + KSWZ((which) * 32 + r32, (cbase + (d0) * 16 + hi * 8) * 2)))
; #define SWRITEB(b) do { *(bf16x8*)(V_lds + (b) * SHM_V + vst0) = vsB0; *(bf16x8*)(V_lds + (b) * SHM_V + vst1) = vsB1; const int kc = sc * 2; \
;     *(bf16x8*)(K_lds + (b) * SHM_K + KSWZ(sr, kc)) = ksB0; *(bf16x8*)(K_lds + (b) * SHM_K + KSWZ(32 + sr, kc)) = ksB1; } while (0)
; #define SWAIT() asm volatile("s_waitcnt vmcnt(4)" ::: "memory")
; __device__ __forceinline__ void qk_only(f32x16& p0, f32x16& p1, const char* Ks, const bf16x8* qr, int r32, int hi, int cbase) {
; #pragma unroll
;   for (int d0 = 0; d0 < 4; ++d0) { const bf16x8 b0 = KFRAG(d0, 0), b1 = KFRAG(d0, 1);
;     p0 = __builtin_amdgcn_mfma_f32_32x32x16_bf16(b0, qr[d0], p0, 0, 0, 0); p1 = __builtin_amdgcn_mfma_f32_32x32x16_bf16(b1, qr[d0], p1, 0, 0, 0); }
; }
; __device__ __forceinline__ void attn_unit(const bf16* __restrict__ P, bf16* __restrict__ MIXIN, const float* __restrict__ gn, int seq0, int h, int q0, int nt, float kmax0, float kmax1, float slope, float lam, char* lds) {
;     ...
;   sc_init(pA0, pA1, DQ(t0), nsl2, m_reg, SIDE(t0)); qk_only(pA0, pA1, K_lds, qr, r32, hi, cbase);
; #pragma unroll
;   for (int r = 0; r < 16; ++r) { pA0[r] = __builtin_amdgcn_exp2f(pA0[r]); pA1[r] = __builtin_amdgcn_exp2f(pA1[r]); }
;   SWAIT(); SWRITEB(1); __syncthreads();
.LBB0_320:
	v_lshlrev_b32_e32 v34, 4, v36
	v_lshlrev_b32_e32 v232, 8, v36
	v_lshlrev_b32_e32 v32, 1, v32
	v_and_b32_e32 v34, 0x70, v34
	v_add_u32_e32 v35, 0, v232
	v_bitop3_b32 v236, v32, v34, v176 bitop3:0x36
	v_add_u32_e32 v241, v35, v236
	ds_read_b128 v[38:41], v241 offset:32768
	ds_read_b128 v[42:45], v241 offset:40960
	s_waitcnt lgkmcnt(1)
	v_mfma_f32_32x32x16_bf16 v[16:31], v[38:41], v[132:135], v[16:31]
	v_or_b32_e32 v32, v32, v176
	v_bitop3_b32 v235, v32, v34, 32 bitop3:0x36
	v_add_u32_e32 v242, v35, v235
	v_bitop3_b32 v234, v32, v34, 64 bitop3:0x36
	v_add_u32_e32 v243, v35, v234
	s_movk_i32 s6, 0x60
	v_bitop3_b32 v233, v32, v34, s6 bitop3:0x36
	s_waitcnt lgkmcnt(0)
	v_mfma_f32_32x32x16_bf16 v[0:15], v[42:45], v[132:135], v[0:15]
	ds_read_b128 v[38:41], v242 offset:32768
	ds_read_b128 v[42:45], v242 offset:40960
	v_lshlrev_b32_e32 v32, 4, v33
	v_add_u32_e32 v244, v35, v233
	v_lshlrev_b32_e32 v36, 3, v33
	v_and_b32_e32 v32, 0xc0, v32
	s_cmp_lg_u32 0, -1
	s_cselect_b32 s6, 0, 0
	s_waitcnt lgkmcnt(1)
	v_mfma_f32_32x32x16_bf16 v[16:31], v[38:41], v[128:131], v[16:31]
	s_andn2_b64 vcc, exec, s[0:1]
	s_waitcnt lgkmcnt(0)
	v_mfma_f32_32x32x16_bf16 v[0:15], v[42:45], v[128:131], v[0:15]
	ds_read_b128 v[38:41], v243 offset:32768
	ds_read_b128 v[42:45], v243 offset:40960
	s_waitcnt lgkmcnt(1)
	v_mfma_f32_32x32x16_bf16 v[16:31], v[38:41], v[140:143], v[16:31]
	ds_read_b128 v[38:41], v244 offset:32768
	s_waitcnt lgkmcnt(1)
	v_mfma_f32_32x32x16_bf16 v[0:15], v[42:45], v[140:143], v[0:15]
	v_and_or_b32 v42, v36, 24, v32
	v_lshlrev_b32_e32 v43, 1, v33
	ds_read_b128 v[32:35], v244 offset:40960
	v_and_b32_e32 v36, 0x100, v36
	s_waitcnt vmcnt(4)
	s_waitcnt vmcnt(3)
	ds_write_b128 v239, v[160:163] offset:16384
	s_waitcnt vmcnt(1)
	ds_write_b128 v240, v[168:171] offset:16384
	ds_write_b128 v237, v[164:167] offset:49152
	s_waitcnt vmcnt(0)
	ds_write_b128 v238, v[172:175] offset:49152
	s_waitcnt lgkmcnt(0)
	v_mfma_f32_32x32x16_bf16 v[16:31], v[38:41], v[136:139], v[16:31]
	v_and_b32_e32 v38, 32, v43
	v_or3_b32 v176, v42, v38, v36
	v_add_u32_e32 v230, s6, v176
	s_barrier
	s_nop 7
	v_exp_f32_e32 v80, v16
	v_mfma_f32_32x32x16_bf16 v[0:15], v[32:35], v[136:139], v[0:15]
	v_exp_f32_e32 v81, v17
	v_exp_f32_e32 v82, v18
	v_exp_f32_e32 v83, v19
	v_exp_f32_e32 v84, v20
	v_exp_f32_e32 v85, v21
	v_exp_f32_e32 v86, v22
	v_exp_f32_e32 v87, v23
	s_nop 4
	v_exp_f32_e32 v64, v0
	v_exp_f32_e32 v65, v1
	v_exp_f32_e32 v66, v2
	v_exp_f32_e32 v67, v3
	v_exp_f32_e32 v68, v4
	v_exp_f32_e32 v69, v5
	v_exp_f32_e32 v70, v6
	v_exp_f32_e32 v71, v7
	v_exp_f32_e32 v88, v24
	v_exp_f32_e32 v72, v8
	v_exp_f32_e32 v89, v25
	v_exp_f32_e32 v73, v9
	v_exp_f32_e32 v90, v26
	v_exp_f32_e32 v74, v10
	v_exp_f32_e32 v91, v27
	v_exp_f32_e32 v75, v11
	v_exp_f32_e32 v92, v28
	v_exp_f32_e32 v76, v12
	v_exp_f32_e32 v93, v29
	v_exp_f32_e32 v77, v13
	v_exp_f32_e32 v94, v30
	v_exp_f32_e32 v78, v14
	v_exp_f32_e32 v95, v31
	v_exp_f32_e32 v79, v15
	v_mov_b32_e32 v15, 0
	s_cbranch_vccnz .LBB0_335
	s_cmp_lg_u32 0, -1
	s_cselect_b32 s0, 0, 0
	v_xor_b32_e32 v186, 0x80000000, v182
	s_addk_i32 s0, 0x4000
	v_mov_b32_e32 v231, 0
	v_mov_b32_e32 v222, v214
	v_add_u32_e32 v245, s0, v176
	v_mov_b32_e32 v188, v180
	v_mov_b32_e32 v189, v180
	v_mov_b32_e32 v187, v186
	v_mov_b32_e32 v190, v180
	v_mov_b32_e32 v191, v180
	v_mov_b32_e32 v192, v186
	v_mov_b32_e32 v193, v186
	v_mov_b32_e32 v194, v186
	v_mov_b32_e32 v195, v186
	v_mov_b32_e32 v196, v186
	v_mov_b32_e32 v197, v186
	v_mov_b32_e32 v198, v186
	v_mov_b32_e32 v199, v186
	v_mov_b32_e32 v200, v186
	v_mov_b32_e32 v201, v186
	v_mov_b32_e32 v202, v186
	v_mov_b32_e32 v203, v186
	v_mov_b32_e32 v204, v186
	v_mov_b32_e32 v205, v186
	v_mov_b32_e32 v206, v186
	v_mov_b32_e32 v207, v186
	v_add_u32_e32 v246, 0x120, v37
	v_mov_b32_e32 v48, 0
	v_mov_b32_e32 v49, v231
	v_mov_b32_e32 v50, v231
	v_mov_b32_e32 v51, v231
	v_mov_b32_e32 v52, v231
	v_mov_b32_e32 v53, v231
	v_mov_b32_e32 v54, v231
	v_mov_b32_e32 v55, v231
	v_mov_b32_e32 v56, v231
	v_mov_b32_e32 v57, v231
	v_mov_b32_e32 v58, v231
	v_mov_b32_e32 v59, v231
	v_mov_b32_e32 v60, v231
	v_mov_b32_e32 v61, v231
	v_mov_b32_e32 v62, v231
	v_mov_b32_e32 v63, v231
	v_mov_b32_e32 v32, 0
	v_mov_b32_e32 v33, v231
	v_mov_b32_e32 v34, v231
	v_mov_b32_e32 v35, v231
	v_mov_b32_e32 v36, v231
	v_mov_b32_e32 v37, v231
	v_mov_b32_e32 v38, v231
	v_mov_b32_e32 v39, v231
	v_mov_b32_e32 v40, v231
	v_mov_b32_e32 v41, v231
	v_mov_b32_e32 v42, v231
	v_mov_b32_e32 v43, v231
	v_mov_b32_e32 v44, v231
	v_mov_b32_e32 v45, v231
	v_mov_b32_e32 v46, v231
	v_mov_b32_e32 v47, v231
	v_mov_b32_e32 v16, 0
	v_mov_b32_e32 v17, v231
	v_mov_b32_e32 v18, v231
	v_mov_b32_e32 v19, v231
	v_mov_b32_e32 v20, v231
	v_mov_b32_e32 v21, v231
	v_mov_b32_e32 v22, v231
	v_mov_b32_e32 v23, v231
	v_mov_b32_e32 v24, v231
	v_mov_b32_e32 v25, v231
	v_mov_b32_e32 v26, v231
	v_mov_b32_e32 v27, v231
	v_mov_b32_e32 v28, v231
	v_mov_b32_e32 v29, v231
	v_mov_b32_e32 v30, v231
	v_mov_b32_e32 v31, v231
	v_mov_b32_e32 v0, 0
	v_mov_b32_e32 v1, v231
	v_mov_b32_e32 v2, v231
	v_mov_b32_e32 v3, v231
	v_mov_b32_e32 v4, v231
	v_mov_b32_e32 v5, v231
	v_mov_b32_e32 v6, v231
	v_mov_b32_e32 v7, v231
	v_mov_b32_e32 v8, v231
	v_mov_b32_e32 v9, v231
	v_mov_b32_e32 v10, v231
	v_mov_b32_e32 v11, v231
	v_mov_b32_e32 v12, v231
	v_mov_b32_e32 v13, v231
	v_mov_b32_e32 v14, v231
	v_mov_b32_e32 v15, v231
	s_mov_b32 s101, 1
	s_add_i32 s0, s33, 1
	s_cmp_ge_i32 s0, s3
	s_cbranch_scc1 .LBB0_323

; #define SBAR() __builtin_amdgcn_sched_barrier(0)
; __device__ __forceinline__ void qk_fin(f32x16& n0, f32x16& n1, const char* Ks, const bf16x8* qr, int r32, int hi, int cbase,
;                                        const f32x16& q0, const f32x16& q1, float& l_reg, bf16x8& pa0, bf16x8& pa1, bf16x8& pa2, bf16x8& pa3) {
;   float ps = 0.f;
;   { const bf16x8 k0 = KFRAG(0, 0), k1 = KFRAG(0, 1); n0 = __builtin_amdgcn_mfma_f32_32x32x16_bf16(k0, qr[0], n0, 0, 0, 0); n1 = __builtin_amdgcn_mfma_f32_32x32x16_bf16(k1, qr[0], n1, 0, 0, 0); }
; #pragma unroll
;   for (int r = 0; r < 8; ++r) ps += q0[r];
;   PK4(q0, 0, pa0); asm volatile("" : "+v"(pa0), "+v"(ps)); SBAR();
;   { const bf16x8 k0 = KFRAG(1, 0), k1 = KFRAG(1, 1); n0 = __builtin_amdgcn_mfma_f32_32x32x16_bf16(k0, qr[1], n0, 0, 0, 0); n1 = __builtin_amdgcn_mfma_f32_32x32x16_bf16(k1, qr[1], n1, 0, 0, 0); }
; #pragma unroll
;   for (int r = 8; r < 16; ++r) ps += q0[r];
;   PK4(q0, 8, pa1); asm volatile("" : "+v"(pa1), "+v"(ps)); SBAR();
;   { const bf16x8 k0 = KFRAG(2, 0), k1 = KFRAG(2, 1); n0 = __builtin_amdgcn_mfma_f32_32x32x16_bf16(k0, qr[2], n0, 0, 0, 0); n1 = __builtin_amdgcn_mfma_f32_32x32x16_bf16(k1, qr[2], n1, 0, 0, 0); }
; #pragma unroll
;   for (int r = 0; r < 8; ++r) ps += q1[r];
;   PK4(q1, 0, pa2); asm volatile("" : "+v"(pa2), "+v"(ps)); SBAR();
;   { const bf16x8 k0 = KFRAG(3, 0), k1 = KFRAG(3, 1); n0 = __builtin_amdgcn_mfma_f32_32x32x16_bf16(k0, qr[3], n0, 0, 0, 0); n1 = __builtin_amdgcn_mfma_f32_32x32x16_bf16(k1, qr[3], n1, 0, 0, 0); }
; #pragma unroll
;   for (int r = 8; r < 16; ++r) ps += q1[r];
;   PK4(q1, 8, pa3);
;   { auto rr = __builtin_amdgcn_permlane32_swap(__float_as_uint(ps), __float_as_uint(ps), false, false); ps = __uint_as_float(rr[0]) + __uint_as_float(rr[1]); }
;   l_reg += ps; SBAR();
; }
; __device__ __forceinline__ void attn_unit(const bf16* __restrict__ P, bf16* __restrict__ MIXIN, const float* __restrict__ gn, int seq0, int h, int q0, int nt, float kmax0, float kmax1, float slope, float lam, char* lds) {
;     ...
;     if (j + 2 < t1) SLOADB((j + 2) * 64); SBAR();
;     sc_init(pB0, pB1, DQ(j), nsl2, m_reg, SIDE(j)); SBAR();
;     qk_fin(pB0, pB1, K_lds + SHM_K, qr, r32, hi, cbase, pA0, pA1, l_reg, pa0, pa1, pa2, pa3);
;     pv_exp(o, vb0, pa0, pa1, pa2, pa3, pB0, pB1);
.LBB0_326:
	ds_read_b128 v[248:251], v241 offset:49152
	ds_read_b128 v[214:217], v241 offset:57344
	v_add_f32_e32 v179, 0, v80
	v_add_f32_e32 v179, v81, v179
	v_cvt_pk_bf16_f32 v80, v80, v81
	v_add_f32_e32 v179, v82, v179
	v_add_f32_e32 v179, v83, v179
	v_cvt_pk_bf16_f32 v81, v82, v83
	v_add_f32_e32 v179, v84, v179
	v_add_f32_e32 v179, v85, v179
	v_cvt_pk_bf16_f32 v82, v84, v85
	v_add_f32_e32 v179, v86, v179
	v_add_f32_e32 v179, v87, v179
	v_cvt_pk_bf16_f32 v83, v86, v87
	s_nop 1
	v_permlane32_swap_b32_e32 v80, v82
	v_permlane32_swap_b32_e32 v81, v83
	s_waitcnt lgkmcnt(1)
	v_mfma_f32_32x32x16_bf16 v[112:127], v[248:251], v[132:135], v[112:127]
	s_waitcnt lgkmcnt(0)
	v_mfma_f32_32x32x16_bf16 v[96:111], v[214:217], v[132:135], v[96:111]
	s_cmp_lg_u32 s101, 0
	s_cbranch_scc1 .Lattn_nlB
	global_load_dwordx4 v[160:163], v[164:165], off offset:2048
	global_load_dwordx4 v[164:167], v[164:165], off offset:1024
	global_load_dwordx4 v[168:171], v[172:173], off offset:2048
	global_load_dwordx4 v[172:175], v[172:173], off offset:1024
.Lattn_nlB:
	ds_read_b128 v[248:251], v242 offset:49152
	ds_read_b128 v[214:217], v242 offset:57344
	v_add_f32_e32 v179, v88, v179
	v_add_f32_e32 v179, v89, v179
	v_cvt_pk_bf16_f32 v84, v88, v89
	v_add_f32_e32 v179, v90, v179
	v_add_f32_e32 v179, v91, v179
	v_cvt_pk_bf16_f32 v85, v90, v91
	v_add_f32_e32 v179, v92, v179
	v_add_f32_e32 v179, v93, v179
	v_cvt_pk_bf16_f32 v86, v92, v93
	v_add_f32_e32 v179, v94, v179
	v_add_f32_e32 v179, v95, v179
	v_cvt_pk_bf16_f32 v87, v94, v95
	s_nop 1
	v_permlane32_swap_b32_e32 v84, v86
	v_permlane32_swap_b32_e32 v85, v87
	s_waitcnt lgkmcnt(1)
	v_mfma_f32_32x32x16_bf16 v[112:127], v[248:251], v[128:131], v[112:127]
	s_waitcnt lgkmcnt(0)
	v_mfma_f32_32x32x16_bf16 v[96:111], v[214:217], v[128:131], v[96:111]
	ds_read_b128 v[248:251], v243 offset:49152
	ds_read_b128 v[214:217], v243 offset:57344
	v_add_f32_e32 v179, v64, v179
	v_add_f32_e32 v179, v65, v179
	v_cvt_pk_bf16_f32 v64, v64, v65
	v_add_f32_e32 v179, v66, v179
	v_add_f32_e32 v179, v67, v179
	v_cvt_pk_bf16_f32 v65, v66, v67
	v_add_f32_e32 v179, v68, v179
	v_add_f32_e32 v179, v69, v179
	v_cvt_pk_bf16_f32 v66, v68, v69
	v_add_f32_e32 v179, v70, v179
	v_add_f32_e32 v179, v71, v179
	v_cvt_pk_bf16_f32 v67, v70, v71
	s_nop 1
	v_permlane32_swap_b32_e32 v64, v66
	v_permlane32_swap_b32_e32 v65, v67
	s_waitcnt lgkmcnt(1)
	v_mfma_f32_32x32x16_bf16 v[112:127], v[248:251], v[140:143], v[112:127]
	s_waitcnt lgkmcnt(0)
	v_mfma_f32_32x32x16_bf16 v[96:111], v[214:217], v[140:143], v[96:111]
	ds_read_b128 v[248:251], v244 offset:49152
	ds_read_b128 v[214:217], v244 offset:57344
	v_add_f32_e32 v179, v72, v179
	v_add_f32_e32 v179, v73, v179
	v_cvt_pk_bf16_f32 v68, v72, v73
	v_add_f32_e32 v179, v74, v179
	v_add_f32_e32 v179, v75, v179
	v_cvt_pk_bf16_f32 v69, v74, v75
	v_add_f32_e32 v179, v76, v179
	v_add_f32_e32 v179, v77, v179
	v_cvt_pk_bf16_f32 v70, v76, v77
	v_add_f32_e32 v179, v78, v179
	v_add_f32_e32 v247, v79, v179
	v_cvt_pk_bf16_f32 v71, v78, v79
	s_nop 1
	v_permlane32_swap_b32_e32 v68, v70
	v_permlane32_swap_b32_e32 v69, v71
	s_waitcnt lgkmcnt(1)
	v_mfma_f32_32x32x16_bf16 v[112:127], v[248:251], v[136:139], v[112:127]
	s_waitcnt lgkmcnt(0)
	v_mfma_f32_32x32x16_bf16 v[96:111], v[214:217], v[136:139], v[96:111]
	v_mov_b32_e32 v248, v247
	s_nop 1
	v_permlane32_swap_b32_e32 v247, v248
	ds_read_b64_tr_b16 v[72:73], v230 offset:0
	ds_read_b64_tr_b16 v[74:75], v230 offset:2048
	ds_read_b64_tr_b16 v[76:77], v230 offset:4096
	ds_read_b64_tr_b16 v[78:79], v230 offset:6144
	ds_read_b64_tr_b16 v[88:89], v230 offset:8192
	ds_read_b64_tr_b16 v[90:91], v230 offset:10240
	ds_read_b64_tr_b16 v[92:93], v230 offset:12288
	ds_read_b64_tr_b16 v[94:95], v230 offset:14336
	s_waitcnt lgkmcnt(4)
	v_mfma_f32_32x32x16_bf16 v[48:63], v[80:83], v[72:75], v[48:63]
	v_exp_f32_e32 v112, v112
	v_exp_f32_e32 v113, v113
	v_mfma_f32_32x32x16_bf16 v[48:63], v[84:87], v[76:79], v[48:63]
	ds_read_b64_tr_b16 v[72:73], v230 offset:512
	ds_read_b64_tr_b16 v[74:75], v230 offset:2560
	ds_read_b64_tr_b16 v[76:77], v230 offset:4608
	ds_read_b64_tr_b16 v[78:79], v230 offset:6656
	v_exp_f32_e32 v114, v114
	v_exp_f32_e32 v115, v115
	s_waitcnt lgkmcnt(4)
	v_mfma_f32_32x32x16_bf16 v[48:63], v[64:67], v[88:91], v[48:63]
	v_exp_f32_e32 v116, v116
	v_exp_f32_e32 v117, v117
	v_mfma_f32_32x32x16_bf16 v[48:63], v[68:71], v[92:95], v[48:63]
	ds_read_b64_tr_b16 v[88:89], v230 offset:8704
	ds_read_b64_tr_b16 v[90:91], v230 offset:10752
	ds_read_b64_tr_b16 v[92:93], v230 offset:12800
	ds_read_b64_tr_b16 v[94:95], v230 offset:14848
	v_exp_f32_e32 v118, v118
	v_exp_f32_e32 v119, v119
	s_waitcnt lgkmcnt(4)
; #define SBAR() __builtin_amdgcn_sched_barrier(0)
; __device__ __forceinline__ void sc_init(f32x16& p0, f32x16& p1, float dq, float nsl2, float m_ref, int side) {
;   if (side != 0) { const float sg = (float)side; const float base0 = fmaf(sg * nsl2, dq, -m_ref), base1 = base0 - sg * 32.f * nsl2;
; #pragma unroll
;     for (int r = 0; r < 16; ++r) { const float c = -sg * nsl2 * (float)((r & 3) + 8 * (r >> 2)); p0[r] = base0 + c; p1[r] = base1 + c; }
;   } else {
; #pragma unroll
;     for (int r = 0; r < 16; ++r) { const float kv = (float)((r & 3) + 8 * (r >> 2)); const float d0 = dq - kv, d1 = d0 - 32.f;
;       p0[r] = fmaf(nsl2, __builtin_fabsf(d0), -m_ref); p1[r] = fmaf(nsl2, __builtin_fabsf(d1), -m_ref); }
;   }
; }
; __device__ __forceinline__ void pv_exp(f32x16* o, int vb, bf16x8 pa0, bf16x8 pa1, bf16x8 pa2, bf16x8 pa3, f32x16& n0, f32x16& n1) {
;   pv_one<0>(o[0], vb, pa0, pa1, pa2, pa3);
; #pragma unroll
;   for (int r = 0; r < 8; ++r) n0[r] = __builtin_amdgcn_exp2f(n0[r]);
;   asm volatile("" : "+v"(n0)); SBAR(); pv_one<1>(o[1], vb, pa0, pa1, pa2, pa3);
; #pragma unroll
;   for (int r = 8; r < 16; ++r) n0[r] = __builtin_amdgcn_exp2f(n0[r]);
;   asm volatile("" : "+v"(n0)); SBAR(); pv_one<2>(o[2], vb, pa0, pa1, pa2, pa3);
; #pragma unroll
;   for (int r = 0; r < 8; ++r) n1[r] = __builtin_amdgcn_exp2f(n1[r]);
;   asm volatile("" : "+v"(n1)); SBAR(); pv_one<3>(o[3], vb, pa0, pa1, pa2, pa3);
; #pragma unroll
;   for (int r = 8; r < 16; ++r) n1[r] = __builtin_amdgcn_exp2f(n1[r]);
;   asm volatile("" : "+v"(n1)); SBAR();
; }
	v_mfma_f32_32x32x16_bf16 v[32:47], v[80:83], v[72:75], v[32:47]
	v_exp_f32_e32 v120, v120
	v_exp_f32_e32 v121, v121
	v_mfma_f32_32x32x16_bf16 v[32:47], v[84:87], v[76:79], v[32:47]
	ds_read_b64_tr_b16 v[72:73], v230 offset:1024
	ds_read_b64_tr_b16 v[74:75], v230 offset:3072
	ds_read_b64_tr_b16 v[76:77], v230 offset:5120
	ds_read_b64_tr_b16 v[78:79], v230 offset:7168
	v_exp_f32_e32 v122, v122
	v_exp_f32_e32 v123, v123
	s_waitcnt lgkmcnt(4)
	v_mfma_f32_32x32x16_bf16 v[32:47], v[64:67], v[88:91], v[32:47]
	v_exp_f32_e32 v124, v124
	v_exp_f32_e32 v125, v125
	v_mfma_f32_32x32x16_bf16 v[32:47], v[68:71], v[92:95], v[32:47]
	ds_read_b64_tr_b16 v[88:89], v230 offset:9216
	ds_read_b64_tr_b16 v[90:91], v230 offset:11264
	ds_read_b64_tr_b16 v[92:93], v230 offset:13312
	ds_read_b64_tr_b16 v[94:95], v230 offset:15360
	v_exp_f32_e32 v126, v126
	v_exp_f32_e32 v127, v127
	s_waitcnt lgkmcnt(4)
	v_mfma_f32_32x32x16_bf16 v[16:31], v[80:83], v[72:75], v[16:31]
	v_exp_f32_e32 v96, v96
	v_exp_f32_e32 v97, v97
	v_mfma_f32_32x32x16_bf16 v[16:31], v[84:87], v[76:79], v[16:31]
	ds_read_b64_tr_b16 v[72:73], v230 offset:1536
	ds_read_b64_tr_b16 v[74:75], v230 offset:3584
	ds_read_b64_tr_b16 v[76:77], v230 offset:5632
	ds_read_b64_tr_b16 v[78:79], v230 offset:7680
	v_exp_f32_e32 v98, v98
	v_exp_f32_e32 v99, v99
	s_waitcnt lgkmcnt(4)
	v_mfma_f32_32x32x16_bf16 v[16:31], v[64:67], v[88:91], v[16:31]
	v_exp_f32_e32 v100, v100
	v_exp_f32_e32 v101, v101
	v_mfma_f32_32x32x16_bf16 v[16:31], v[68:71], v[92:95], v[16:31]
	ds_read_b64_tr_b16 v[88:89], v230 offset:9728
	ds_read_b64_tr_b16 v[90:91], v230 offset:11776
	ds_read_b64_tr_b16 v[92:93], v230 offset:13824
	ds_read_b64_tr_b16 v[94:95], v230 offset:15872
	v_exp_f32_e32 v102, v102
	v_exp_f32_e32 v103, v103
	s_waitcnt lgkmcnt(4)
	v_mfma_f32_32x32x16_bf16 v[0:15], v[80:83], v[72:75], v[0:15]
	v_exp_f32_e32 v104, v104
	v_exp_f32_e32 v105, v105
	v_mfma_f32_32x32x16_bf16 v[0:15], v[84:87], v[76:79], v[0:15]
	v_exp_f32_e32 v106, v106
	v_exp_f32_e32 v107, v107
	s_waitcnt lgkmcnt(0)
	v_mfma_f32_32x32x16_bf16 v[0:15], v[64:67], v[88:91], v[0:15]
	v_exp_f32_e32 v108, v108
	v_exp_f32_e32 v109, v109
	v_mfma_f32_32x32x16_bf16 v[0:15], v[68:71], v[92:95], v[0:15]
	v_exp_f32_e32 v110, v110
	v_exp_f32_e32 v111, v111
	s_add_i32 s6, s33, -1
	s_cmp_ge_u32 s6, s73
	v_cvt_f32_i32_e32 v65, s33
	s_cselect_b64 s[6:7], -1, 0
	s_cmp_ge_u32 s33, s72
	v_cndmask_b32_e64 v64, 0, -1, s[6:7]
	s_cselect_b64 vcc, -1, 0
	v_cndmask_b32_e32 v64, 1, v64, vcc
	v_cmp_ne_u32_e32 vcc, 0, v64
	v_fmamk_f32 v208, v65, 0xc2800000, v184
	s_cbranch_vccz .Lattn_i2_ovl
	v_cvt_f32_i32_e32 v64, v64
	v_mul_f32_e32 v66, v180, v64
	v_mul_f32_e32 v65, 0x42000000, v64
	v_xor_b32_e32 v64, 0x80000000, v64
	v_fma_f32 v179, v66, v208, -v182
	v_pk_mul_f32 v[214:215], v[188:189], v[64:65]
	v_pk_fma_f32 v[216:217], v[188:189], v[64:65], v[178:179] neg_lo:[1,0,0] neg_hi:[1,0,0]
	v_mul_f32_e32 v80, 0, v214
	v_pk_mul_f32 v[82:83], v[214:215], s[14:15]
	v_mov_b32_e32 v81, v214
	v_pk_add_f32 v[64:65], v[80:81], v[216:217] op_sel:[0,1]
	v_pk_fma_f32 v[66:67], v[214:215], s[48:49], v[216:217] op_sel:[0,0,1] op_sel_hi:[0,1,1]
	v_pk_fma_f32 v[68:69], v[214:215], s[50:51], v[216:217] op_sel:[0,0,1] op_sel_hi:[0,1,1]
	v_pk_fma_f32 v[70:71], v[214:215], s[58:59], v[216:217] op_sel:[0,0,1] op_sel_hi:[0,1,1]
	v_pk_fma_f32 v[72:73], v[214:215], s[64:65], v[216:217] op_sel:[0,0,1] op_sel_hi:[0,1,1]
	v_pk_fma_f32 v[74:75], v[214:215], s[80:81], v[216:217] op_sel:[0,0,1] op_sel_hi:[0,1,1]
	v_pk_fma_f32 v[76:77], v[214:215], s[82:83], v[216:217] op_sel:[0,0,1] op_sel_hi:[0,1,1]
	v_pk_fma_f32 v[78:79], v[214:215], s[14:15], v[216:217] op_sel:[0,0,1] op_sel_hi:[1,1,0]
	v_mul_f32_e32 v83, 0x41d80000, v214
	v_mov_b32_e32 v216, v179
	v_pk_add_f32 v[94:95], v[216:217], v[82:83] op_sel_hi:[0,1]
	v_pk_add_f32 v[80:81], v[216:217], v[80:81] op_sel_hi:[0,1]
	v_pk_fma_f32 v[92:93], v[214:215], s[82:83], v[216:217] op_sel_hi:[0,1,0]
	v_pk_fma_f32 v[90:91], v[214:215], s[80:81], v[216:217] op_sel_hi:[0,1,0]
	v_pk_fma_f32 v[88:89], v[214:215], s[64:65], v[216:217] op_sel_hi:[0,1,0]
	v_pk_fma_f32 v[86:87], v[214:215], s[58:59], v[216:217] op_sel_hi:[0,1,0]
	v_pk_fma_f32 v[84:85], v[214:215], s[50:51], v[216:217] op_sel_hi:[0,1,0]
	v_pk_fma_f32 v[82:83], v[214:215], s[48:49], v[216:217] op_sel_hi:[0,1,0]
	v_fmac_f32_e32 v217, 0x41d80000, v214
	v_mov_b32_e32 v79, v217
	s_branch .Lattn_i2_done

; #define SBAR() __builtin_amdgcn_sched_barrier(0)
; #define KFRAG(d0, which) (*reinterpret_cast<const bf16x8*>(Ks + KSWZ((which) * 32 + r32, (cbase + (d0) * 16 + hi * 8) * 2)))
; #define SLOADA(k0) do { vsA0 = *(const bf16x8*)(&Vh[(size_t)((k0) + sr) * LDP + sc]); vsA1 = *(const bf16x8*)(&Vh[(size_t)((k0) + 32 + sr) * LDP + sc]); \
;     ksA0 = *(const bf16x8*)(&Kh[(size_t)((k0) + sr) * LDP + sc]); ksA1 = *(const bf16x8*)(&Kh[(size_t)((k0) + 32 + sr) * LDP + sc]); } while (0)
; #define SWAIT() asm volatile("s_waitcnt vmcnt(4)" ::: "memory")
; __device__ __forceinline__ void qk_fin(f32x16& n0, f32x16& n1, const char* Ks, const bf16x8* qr, int r32, int hi, int cbase,
;                                        const f32x16& q0, const f32x16& q1, float& l_reg, bf16x8& pa0, bf16x8& pa1, bf16x8& pa2, bf16x8& pa3) {
;   float ps = 0.f;
;   { const bf16x8 k0 = KFRAG(0, 0), k1 = KFRAG(0, 1); n0 = __builtin_amdgcn_mfma_f32_32x32x16_bf16(k0, qr[0], n0, 0, 0, 0); n1 = __builtin_amdgcn_mfma_f32_32x32x16_bf16(k1, qr[0], n1, 0, 0, 0); }
; #pragma unroll
;   for (int r = 0; r < 8; ++r) ps += q0[r];
;   PK4(q0, 0, pa0); asm volatile("" : "+v"(pa0), "+v"(ps)); SBAR();
;   { const bf16x8 k0 = KFRAG(1, 0), k1 = KFRAG(1, 1); n0 = __builtin_amdgcn_mfma_f32_32x32x16_bf16(k0, qr[1], n0, 0, 0, 0); n1 = __builtin_amdgcn_mfma_f32_32x32x16_bf16(k1, qr[1], n1, 0, 0, 0); }
; #pragma unroll
;   for (int r = 8; r < 16; ++r) ps += q0[r];
;   PK4(q0, 8, pa1); asm volatile("" : "+v"(pa1), "+v"(ps)); SBAR();
;   { const bf16x8 k0 = KFRAG(2, 0), k1 = KFRAG(2, 1); n0 = __builtin_amdgcn_mfma_f32_32x32x16_bf16(k0, qr[2], n0, 0, 0, 0); n1 = __builtin_amdgcn_mfma_f32_32x32x16_bf16(k1, qr[2], n1, 0, 0, 0); }
; #pragma unroll
;   for (int r = 0; r < 8; ++r) ps += q1[r];
;   PK4(q1, 0, pa2); asm volatile("" : "+v"(pa2), "+v"(ps)); SBAR();
; __device__ __forceinline__ void attn_unit(const bf16* __restrict__ P, bf16* __restrict__ MIXIN, const float* __restrict__ gn, int seq0, int h, int q0, int nt, float kmax0, float kmax1, float slope, float lam, char* lds) {
;     ...
;     __syncthreads(); SWAIT(); SWRITEA(0); __syncthreads();
;     if (j + 3 < t1) SLOADA((j + 3) * 64); SBAR();
;     sc_init(pA0, pA1, DQ(j + 1), nsl2, m_reg, SIDE(j + 1)); SBAR();
;     qk_fin(pA0, pA1, K_lds, qr, r32, hi, cbase, pB0, pB1, l_reg, pa0, pa1, pa2, pa3);
;     pv_exp(o, vb0 + SHM_V, pa0, pa1, pa2, pa3, pA0, pA1);
.Lattn_nocalcA:
	s_waitcnt vmcnt(4)
	ds_write_b128 v237, v[148:151] offset:32768
	ds_write_b128 v238, v[156:159] offset:32768
	s_barrier
	s_waitcnt vmcnt(4)
	s_cmp_ge_i32 s76, s3
	s_cselect_b64 s[0:1], -1, 0
	s_and_b64 vcc, exec, s[0:1]
	ds_write_b128 v239, v[144:147]
	ds_write_b128 v240, v[152:155]
	s_waitcnt lgkmcnt(2)
	s_barrier
	v_mov_b32_e32 v148, v214
	v_mov_b32_e32 v149, v215
	v_mov_b32_e32 v156, v216
	v_mov_b32_e32 v157, v217
.LBB0_328:
.LBB0_331:
	v_add_f32_e32 v179, v247, v248
	v_add_f32_e32 v179, v231, v179
	ds_read_b128 v[214:217], v241 offset:32768
	ds_read_b128 v[248:251], v241 offset:40960
	v_add_f32_e32 v181, 0, v112
	v_add_f32_e32 v181, v113, v181
	v_cvt_pk_bf16_f32 v112, v112, v113
	v_add_f32_e32 v181, v114, v181
	v_add_f32_e32 v181, v115, v181
	v_cvt_pk_bf16_f32 v113, v114, v115
	v_add_f32_e32 v181, v116, v181
	v_add_f32_e32 v181, v117, v181
	v_cvt_pk_bf16_f32 v114, v116, v117
	v_add_f32_e32 v181, v118, v181
	v_add_f32_e32 v181, v119, v181
	v_cvt_pk_bf16_f32 v115, v118, v119
	s_nop 1
	v_permlane32_swap_b32_e32 v112, v114
	v_permlane32_swap_b32_e32 v113, v115
	s_waitcnt lgkmcnt(1)
	v_mfma_f32_32x32x16_bf16 v[80:95], v[214:217], v[132:135], v[80:95]
	s_waitcnt lgkmcnt(0)
	v_mfma_f32_32x32x16_bf16 v[64:79], v[248:251], v[132:135], v[64:79]
	s_cbranch_vccnz .Lattn_nlA
	global_load_dwordx4 v[144:147], v[148:149], off offset:2048
	global_load_dwordx4 v[148:151], v[148:149], off offset:1024
	global_load_dwordx4 v[152:155], v[156:157], off offset:2048
	global_load_dwordx4 v[156:159], v[156:157], off offset:1024
.Lattn_nlA:
	ds_read_b128 v[214:217], v242 offset:32768
	ds_read_b128 v[248:251], v242 offset:40960
	v_add_f32_e32 v181, v120, v181
	v_add_f32_e32 v181, v121, v181
	v_cvt_pk_bf16_f32 v116, v120, v121
	v_add_f32_e32 v181, v122, v181
	v_add_f32_e32 v181, v123, v181
	v_cvt_pk_bf16_f32 v117, v122, v123
	v_add_f32_e32 v181, v124, v181
	v_add_f32_e32 v181, v125, v181
	v_cvt_pk_bf16_f32 v118, v124, v125
	v_add_f32_e32 v181, v126, v181
	v_add_f32_e32 v181, v127, v181
	v_cvt_pk_bf16_f32 v119, v126, v127
	s_nop 1
	v_permlane32_swap_b32_e32 v116, v118
	v_permlane32_swap_b32_e32 v117, v119
	s_waitcnt lgkmcnt(1)
	v_mfma_f32_32x32x16_bf16 v[80:95], v[214:217], v[128:131], v[80:95]
	s_waitcnt lgkmcnt(0)
	v_mfma_f32_32x32x16_bf16 v[64:79], v[248:251], v[128:131], v[64:79]
	ds_read_b128 v[214:217], v243 offset:32768
	ds_read_b128 v[248:251], v243 offset:40960
	v_add_f32_e32 v181, v96, v181
	v_add_f32_e32 v181, v97, v181
	v_cvt_pk_bf16_f32 v96, v96, v97
	v_add_f32_e32 v181, v98, v181
	v_add_f32_e32 v181, v99, v181
	v_cvt_pk_bf16_f32 v97, v98, v99
	v_add_f32_e32 v181, v100, v181
	v_add_f32_e32 v181, v101, v181
	v_cvt_pk_bf16_f32 v98, v100, v101
	v_add_f32_e32 v181, v102, v181
	v_add_f32_e32 v181, v103, v181
	v_cvt_pk_bf16_f32 v99, v102, v103
	s_nop 1
	v_permlane32_swap_b32_e32 v96, v98
	v_permlane32_swap_b32_e32 v97, v99
	s_waitcnt lgkmcnt(1)
	v_mfma_f32_32x32x16_bf16 v[80:95], v[214:217], v[140:143], v[80:95]
	s_waitcnt lgkmcnt(0)
	v_mfma_f32_32x32x16_bf16 v[64:79], v[248:251], v[140:143], v[64:79]
	ds_read_b128 v[214:217], v244 offset:32768
	ds_read_b128 v[248:251], v244 offset:40960
	v_add_f32_e32 v181, v104, v181
	v_add_f32_e32 v181, v105, v181
	v_cvt_pk_bf16_f32 v100, v104, v105
	v_add_f32_e32 v181, v106, v181
	v_add_f32_e32 v181, v107, v181
	v_cvt_pk_bf16_f32 v101, v106, v107
	v_add_f32_e32 v181, v108, v181
	v_add_f32_e32 v181, v109, v181
	v_cvt_pk_bf16_f32 v102, v108, v109
	v_add_f32_e32 v181, v110, v181
	v_add_f32_e32 v120, v111, v181
	v_cvt_pk_bf16_f32 v103, v110, v111
	s_nop 1
	v_permlane32_swap_b32_e32 v100, v102
	v_permlane32_swap_b32_e32 v101, v103
	v_mov_b32_e32 v104, v120
	s_nop 1
	v_permlane32_swap_b32_e32 v120, v104
	v_add_f32_e32 v104, v120, v104
	v_add_f32_e32 v231, v179, v104
	s_waitcnt lgkmcnt(1)
	v_mfma_f32_32x32x16_bf16 v[80:95], v[214:217], v[136:139], v[80:95]
	s_waitcnt lgkmcnt(0)
	v_mfma_f32_32x32x16_bf16 v[64:79], v[248:251], v[136:139], v[64:79]
	s_nop 0
	ds_read_b64_tr_b16 v[104:105], v245 offset:0
	ds_read_b64_tr_b16 v[106:107], v245 offset:2048
	ds_read_b64_tr_b16 v[108:109], v245 offset:4096
	ds_read_b64_tr_b16 v[110:111], v245 offset:6144
	ds_read_b64_tr_b16 v[120:121], v245 offset:8192
	ds_read_b64_tr_b16 v[122:123], v245 offset:10240
	ds_read_b64_tr_b16 v[124:125], v245 offset:12288
	ds_read_b64_tr_b16 v[126:127], v245 offset:14336
	s_waitcnt lgkmcnt(4)
	v_mfma_f32_32x32x16_bf16 v[48:63], v[112:115], v[104:107], v[48:63]
	v_exp_f32_e32 v80, v80
	v_exp_f32_e32 v81, v81
	v_mfma_f32_32x32x16_bf16 v[48:63], v[116:119], v[108:111], v[48:63]
	ds_read_b64_tr_b16 v[104:105], v245 offset:512
	ds_read_b64_tr_b16 v[106:107], v245 offset:2560
	ds_read_b64_tr_b16 v[108:109], v245 offset:4608
	ds_read_b64_tr_b16 v[110:111], v245 offset:6656
	v_exp_f32_e32 v82, v82
	v_exp_f32_e32 v83, v83
	s_waitcnt lgkmcnt(4)
; #define SBAR() __builtin_amdgcn_sched_barrier(0)
; __device__ __forceinline__ void sc_init(f32x16& p0, f32x16& p1, float dq, float nsl2, float m_ref, int side) {
;   if (side != 0) { const float sg = (float)side; const float base0 = fmaf(sg * nsl2, dq, -m_ref), base1 = base0 - sg * 32.f * nsl2;
; #pragma unroll
;     for (int r = 0; r < 16; ++r) { const float c = -sg * nsl2 * (float)((r & 3) + 8 * (r >> 2)); p0[r] = base0 + c; p1[r] = base1 + c; }
;   } else {
; #pragma unroll
;     for (int r = 0; r < 16; ++r) { const float kv = (float)((r & 3) + 8 * (r >> 2)); const float d0 = dq - kv, d1 = d0 - 32.f;
;       p0[r] = fmaf(nsl2, __builtin_fabsf(d0), -m_ref); p1[r] = fmaf(nsl2, __builtin_fabsf(d1), -m_ref); }
;   }
; }
; __device__ __forceinline__ void pv_exp(f32x16* o, int vb, bf16x8 pa0, bf16x8 pa1, bf16x8 pa2, bf16x8 pa3, f32x16& n0, f32x16& n1) {
;   pv_one<0>(o[0], vb, pa0, pa1, pa2, pa3);
; #pragma unroll
;   for (int r = 0; r < 8; ++r) n0[r] = __builtin_amdgcn_exp2f(n0[r]);
;   asm volatile("" : "+v"(n0)); SBAR(); pv_one<1>(o[1], vb, pa0, pa1, pa2, pa3);
; #pragma unroll
;   for (int r = 8; r < 16; ++r) n0[r] = __builtin_amdgcn_exp2f(n0[r]);
;   asm volatile("" : "+v"(n0)); SBAR(); pv_one<2>(o[2], vb, pa0, pa1, pa2, pa3);
; #pragma unroll
;   for (int r = 0; r < 8; ++r) n1[r] = __builtin_amdgcn_exp2f(n1[r]);
;   asm volatile("" : "+v"(n1)); SBAR(); pv_one<3>(o[3], vb, pa0, pa1, pa2, pa3);
; #pragma unroll
;   for (int r = 8; r < 16; ++r) n1[r] = __builtin_amdgcn_exp2f(n1[r]);
;   asm volatile("" : "+v"(n1)); SBAR();
; }
	v_mfma_f32_32x32x16_bf16 v[48:63], v[96:99], v[120:123], v[48:63]
	v_exp_f32_e32 v84, v84
	v_exp_f32_e32 v85, v85
	v_mfma_f32_32x32x16_bf16 v[48:63], v[100:103], v[124:127], v[48:63]
	ds_read_b64_tr_b16 v[120:121], v245 offset:8704
	ds_read_b64_tr_b16 v[122:123], v245 offset:10752
	ds_read_b64_tr_b16 v[124:125], v245 offset:12800
	ds_read_b64_tr_b16 v[126:127], v245 offset:14848
	v_exp_f32_e32 v86, v86
	v_exp_f32_e32 v87, v87
	s_waitcnt lgkmcnt(4)
	v_mfma_f32_32x32x16_bf16 v[32:47], v[112:115], v[104:107], v[32:47]
	v_exp_f32_e32 v88, v88
	v_exp_f32_e32 v89, v89
	v_mfma_f32_32x32x16_bf16 v[32:47], v[116:119], v[108:111], v[32:47]
	ds_read_b64_tr_b16 v[104:105], v245 offset:1024
	ds_read_b64_tr_b16 v[106:107], v245 offset:3072
	ds_read_b64_tr_b16 v[108:109], v245 offset:5120
	ds_read_b64_tr_b16 v[110:111], v245 offset:7168
	v_exp_f32_e32 v90, v90
	v_exp_f32_e32 v91, v91
	s_waitcnt lgkmcnt(4)
	v_mfma_f32_32x32x16_bf16 v[32:47], v[96:99], v[120:123], v[32:47]
	v_exp_f32_e32 v92, v92
	v_exp_f32_e32 v93, v93
	v_mfma_f32_32x32x16_bf16 v[32:47], v[100:103], v[124:127], v[32:47]
	ds_read_b64_tr_b16 v[120:121], v245 offset:9216
	ds_read_b64_tr_b16 v[122:123], v245 offset:11264
	ds_read_b64_tr_b16 v[124:125], v245 offset:13312
	ds_read_b64_tr_b16 v[126:127], v245 offset:15360
	v_exp_f32_e32 v94, v94
	v_exp_f32_e32 v95, v95
	s_waitcnt lgkmcnt(4)
	v_mfma_f32_32x32x16_bf16 v[16:31], v[112:115], v[104:107], v[16:31]
	v_exp_f32_e32 v64, v64
	v_exp_f32_e32 v65, v65
	v_mfma_f32_32x32x16_bf16 v[16:31], v[116:119], v[108:111], v[16:31]
	ds_read_b64_tr_b16 v[104:105], v245 offset:1536
	ds_read_b64_tr_b16 v[106:107], v245 offset:3584
	ds_read_b64_tr_b16 v[108:109], v245 offset:5632
	ds_read_b64_tr_b16 v[110:111], v245 offset:7680
	v_exp_f32_e32 v66, v66
	v_exp_f32_e32 v67, v67
	s_waitcnt lgkmcnt(4)
	v_mfma_f32_32x32x16_bf16 v[16:31], v[96:99], v[120:123], v[16:31]
	v_exp_f32_e32 v68, v68
	v_exp_f32_e32 v69, v69
	v_mfma_f32_32x32x16_bf16 v[16:31], v[100:103], v[124:127], v[16:31]
	ds_read_b64_tr_b16 v[120:121], v245 offset:9728
	ds_read_b64_tr_b16 v[122:123], v245 offset:11776
	ds_read_b64_tr_b16 v[124:125], v245 offset:13824
	ds_read_b64_tr_b16 v[126:127], v245 offset:15872
	v_exp_f32_e32 v70, v70
	v_exp_f32_e32 v71, v71
	s_waitcnt lgkmcnt(4)
	v_mfma_f32_32x32x16_bf16 v[0:15], v[112:115], v[104:107], v[0:15]
	v_exp_f32_e32 v72, v72
	v_exp_f32_e32 v73, v73
	v_mfma_f32_32x32x16_bf16 v[0:15], v[116:119], v[108:111], v[0:15]
	v_exp_f32_e32 v74, v74
	v_exp_f32_e32 v75, v75
	s_waitcnt lgkmcnt(0)
	v_mfma_f32_32x32x16_bf16 v[0:15], v[96:99], v[120:123], v[0:15]
	v_exp_f32_e32 v76, v76
	v_exp_f32_e32 v77, v77
	v_mfma_f32_32x32x16_bf16 v[0:15], v[100:103], v[124:127], v[0:15]
	v_exp_f32_e32 v78, v78
	v_exp_f32_e32 v79, v79
	s_add_i32 s6, s76, -1
	s_cmp_gt_u32 s6, s73
	v_cvt_f32_i32_e32 v97, s6
	s_cselect_b64 s[98:99], -1, 0
	s_cmp_ge_u32 s6, s72
	v_cndmask_b32_e64 v96, 0, -1, s[98:99]
	s_cselect_b64 vcc, -1, 0
	v_cndmask_b32_e32 v96, 1, v96, vcc
	v_cmp_ne_u32_e32 vcc, 0, v96
	v_fmamk_f32 v208, v97, 0xc2800000, v184
	s_cbranch_vccz .Lattn_i1_ovl
	v_cvt_f32_i32_e32 v96, v96
	v_mul_f32_e32 v98, v180, v96
	v_mul_f32_e32 v97, 0x42000000, v96
	v_xor_b32_e32 v96, 0x80000000, v96
	v_fma_f32 v179, v98, v208, -v182
	v_pk_mul_f32 v[214:215], v[188:189], v[96:97]
	v_pk_fma_f32 v[216:217], v[188:189], v[96:97], v[178:179] neg_lo:[1,0,0] neg_hi:[1,0,0]
	v_mul_f32_e32 v112, 0, v214
	v_pk_mul_f32 v[114:115], v[214:215], s[14:15]
	v_mov_b32_e32 v113, v214
	v_pk_add_f32 v[96:97], v[112:113], v[216:217] op_sel:[0,1]
	v_pk_fma_f32 v[98:99], v[214:215], s[48:49], v[216:217] op_sel:[0,0,1] op_sel_hi:[0,1,1]
	v_pk_fma_f32 v[100:101], v[214:215], s[50:51], v[216:217] op_sel:[0,0,1] op_sel_hi:[0,1,1]
	v_pk_fma_f32 v[102:103], v[214:215], s[58:59], v[216:217] op_sel:[0,0,1] op_sel_hi:[0,1,1]
	v_pk_fma_f32 v[104:105], v[214:215], s[64:65], v[216:217] op_sel:[0,0,1] op_sel_hi:[0,1,1]
	v_pk_fma_f32 v[106:107], v[214:215], s[80:81], v[216:217] op_sel:[0,0,1] op_sel_hi:[0,1,1]
	v_pk_fma_f32 v[108:109], v[214:215], s[82:83], v[216:217] op_sel:[0,0,1] op_sel_hi:[0,1,1]
	v_pk_fma_f32 v[110:111], v[214:215], s[14:15], v[216:217] op_sel:[0,0,1] op_sel_hi:[1,1,0]
	v_mul_f32_e32 v115, 0x41d80000, v214
	v_mov_b32_e32 v216, v179
	v_pk_add_f32 v[126:127], v[216:217], v[114:115] op_sel_hi:[0,1]
	v_pk_add_f32 v[112:113], v[216:217], v[112:113] op_sel_hi:[0,1]
	v_pk_fma_f32 v[124:125], v[214:215], s[82:83], v[216:217] op_sel_hi:[0,1,0]
	v_pk_fma_f32 v[122:123], v[214:215], s[80:81], v[216:217] op_sel_hi:[0,1,0]
	v_pk_fma_f32 v[120:121], v[214:215], s[64:65], v[216:217] op_sel_hi:[0,1,0]
	v_pk_fma_f32 v[118:119], v[214:215], s[58:59], v[216:217] op_sel_hi:[0,1,0]
	v_pk_fma_f32 v[116:117], v[214:215], s[50:51], v[216:217] op_sel_hi:[0,1,0]
	v_pk_fma_f32 v[114:115], v[214:215], s[48:49], v[216:217] op_sel_hi:[0,1,0]
	v_fmac_f32_e32 v217, 0x41d80000, v214
	v_mov_b32_e32 v111, v217
	s_branch .Lattn_i1_done

; #define SBAR() __builtin_amdgcn_sched_barrier(0)
; #define SLOADB(k0) do { vsB0 = *(const bf16x8*)(&Vh[(size_t)((k0) + sr) * LDP + sc]); vsB1 = *(const bf16x8*)(&Vh[(size_t)((k0) + 32 + sr) * LDP + sc]); \
;     ksB0 = *(const bf16x8*)(&Kh[(size_t)((k0) + sr) * LDP + sc]); ksB1 = *(const bf16x8*)(&Kh[(size_t)((k0) + 32 + sr) * LDP + sc]); } while (0)
; #define SWRITEB(b) do { *(bf16x8*)(V_lds + (b) * SHM_V + vst0) = vsB0; *(bf16x8*)(V_lds + (b) * SHM_V + vst1) = vsB1; const int kc = sc * 2; \
;     *(bf16x8*)(K_lds + (b) * SHM_K + KSWZ(sr, kc)) = ksB0; *(bf16x8*)(K_lds + (b) * SHM_K + KSWZ(32 + sr, kc)) = ksB1; } while (0)
; #define SWAIT() asm volatile("s_waitcnt vmcnt(4)" ::: "memory")
; __device__ __forceinline__ void attn_unit(const bf16* __restrict__ P, bf16* __restrict__ MIXIN, const float* __restrict__ gn, int seq0, int h, int q0, int nt, float kmax0, float kmax1, float slope, float lam, char* lds) {
;     ...
;     if (j + 2 < t1) SLOADB((j + 2) * 64); SBAR();
;     ...
;     __syncthreads(); SWAIT(); SWRITEB(1); __syncthreads();
;   }
.Lattn_kwB:
	ds_write_b128 v237, v[164:167] offset:49152
	ds_write_b128 v238, v[172:175] offset:49152
	s_barrier
	s_waitcnt vmcnt(4)
	s_and_b64 vcc, exec, s[0:1]
	s_waitcnt vmcnt(3)
	ds_write_b128 v239, v[160:163] offset:16384
	s_waitcnt vmcnt(1)
	ds_write_b128 v240, v[168:171] offset:16384
	s_waitcnt vmcnt(0)
	s_waitcnt lgkmcnt(2)
	s_cbranch_vccz .Lattn_nx
	s_waitcnt lgkmcnt(0)
.Lattn_nx:
	s_barrier
	s_cbranch_vccnz .LBB0_336
	s_mov_b32 s33, s76
	s_add_i32 s0, s33, 1
	s_cmp_ge_i32 s0, s3
	s_cselect_b32 s101, 1, 0
	v_mov_b32_e32 v164, v214
	v_mov_b32_e32 v165, v215
	v_mov_b32_e32 v172, v216
	v_mov_b32_e32 v173, v217
	s_branch .LBB0_326
